# gating (sgu) phase: bias loads hoisted to the top of each item, per-row-block vmcnt(0) waits removed so the next item's loads stay in flight
# baseline (speedup 1.0000x reference)
.LBB0_355:
	s_lshl_b32 s30, s61, 9
	v_lshl_or_b32 v0, v135, 2, s30
	v_mov_b32_e32 v160, v231
	s_lshl_b32 s14, s60, 4
	s_and_b32 s14, s14, 0xffffff80
	v_or_b32_e32 v116, s14, v135
	v_ashrrev_i32_e32 v117, 31, v116
	v_lshlrev_b64 v[116:117], 12, v[116:117]
	v_lshl_add_u64 v[116:117], s[44:45], 0, v[116:117]
	v_lshl_add_u64 v[116:117], v[116:117], 0, s[30:31]
	v_lshl_add_u64 v[116:117], s[46:47], 1, v[116:117]
	v_mov_b32_e32 v131, v1
	v_lshl_add_u64 v[132:133], v[116:117], 0, v[130:131]
	ds_read_u16 v116, v148 offset:516
	ds_read_u16 v117, v148
	ds_read_u16 v118, v148 offset:1032
	ds_read_u16 v119, v148 offset:1548
	ds_read_u16 v124, v148 offset:1556
	ds_read_u16 v125, v148 offset:1040
	ds_read_u16 v126, v148 offset:524
	ds_read_u16 v127, v148 offset:8
	s_waitcnt lgkmcnt(6)
	v_lshl_or_b32 v120, v116, 16, v117
	s_waitcnt lgkmcnt(4)
	v_lshl_or_b32 v121, v119, 16, v118
	ds_read_u16 v116, v148 offset:2064
	ds_read_u16 v117, v148 offset:2580
	ds_read_u16 v118, v148 offset:3096
	ds_read_u16 v119, v148 offset:3612
	ds_read_u16 v131, v148 offset:3620
	ds_read_u16 v152, v148 offset:3104
	ds_read_u16 v153, v148 offset:2588
	ds_read_u16 v154, v148 offset:2072
	s_waitcnt lgkmcnt(6)
	v_lshl_or_b32 v122, v117, 16, v116
	s_waitcnt lgkmcnt(4)
	v_lshl_or_b32 v123, v119, 16, v118
	v_lshl_or_b32 v116, v126, 16, v127
	v_lshl_or_b32 v117, v124, 16, v125
	s_waitcnt lgkmcnt(0)
	v_lshl_or_b32 v118, v153, 16, v154
	v_lshl_or_b32 v119, v131, 16, v152
	ds_read_u16 v131, v148 offset:16512
	ds_read_u16 v161, v148 offset:17028
	ds_read_u16 v162, v148 offset:17544
	ds_read_u16 v163, v148 offset:18060
	ds_read_u16 v164, v148 offset:18068
	ds_read_u16 v165, v148 offset:17552
	ds_read_u16 v166, v148 offset:17036
	ds_read_u16 v167, v148 offset:16520
	ds_read_u16 v168, v148 offset:18576
	ds_read_u16 v169, v148 offset:19092
	ds_read_u16 v170, v148 offset:19608
	ds_read_u16 v171, v148 offset:20124
	ds_read_u16 v172, v148 offset:20132
	ds_read_u16 v173, v148 offset:19616
	ds_read_u16 v174, v148 offset:19100
	ds_read_u16 v175, v148 offset:18584
	ds_read_u16 v176, v148 offset:33024
	ds_read_u16 v177, v148 offset:33540
	ds_read_u16 v178, v148 offset:34056
	ds_read_u16 v179, v148 offset:34572
	ds_read_u16 v180, v148 offset:34580
	ds_read_u16 v181, v148 offset:34064
	ds_read_u16 v182, v148 offset:33548
	ds_read_u16 v183, v148 offset:33032
	ds_read_u16 v185, v148 offset:35088
	ds_read_u16 v186, v148 offset:35604
	ds_read_u16 v187, v148 offset:36120
	ds_read_u16 v188, v148 offset:36636
	ds_read_u16 v189, v148 offset:36644
	ds_read_u16 v190, v148 offset:36128
	ds_read_u16 v191, v148 offset:35612
	ds_read_u16 v192, v148 offset:35096
	ds_read_b128 v[124:127], v151
	ds_read_u16 v193, v148 offset:49536
	ds_read_u16 v194, v148 offset:50052
	ds_read_u16 v195, v148 offset:50568
	ds_read_u16 v196, v148 offset:51084
	ds_read_u16 v197, v148 offset:51092
	ds_read_u16 v198, v148 offset:50576
	ds_read_u16 v199, v148 offset:50060
	ds_read_u16 v200, v148 offset:49544
	s_waitcnt lgkmcnt(8)
	v_mfma_f32_16x16x32_bf16 v[152:155], v[120:123], v[124:127], 0
	v_lshlrev_b32_e32 v209, 16, v80
	v_and_b32_e32 v80, 0xffff0000, v80
	ds_read_u16 v201, v148 offset:51600
	ds_read_u16 v202, v148 offset:52116
	ds_read_u16 v203, v148 offset:52632
	ds_read_u16 v204, v148 offset:53148
	ds_read_u16 v205, v148 offset:53156
	ds_read_u16 v206, v148 offset:52640
	ds_read_u16 v207, v148 offset:52124
	ds_read_u16 v208, v148 offset:51608
	v_mfma_f32_16x16x32_bf16 v[124:127], v[116:119], v[124:127], 0
	v_and_b32_e32 v210, 0xffff0000, v79
	v_and_b32_e32 v211, 0xffff0000, v72
	v_lshlrev_b32_e32 v212, 16, v73
	v_and_b32_e32 v213, 0xffff0000, v73
	v_lshlrev_b32_e32 v214, 16, v74
	v_and_b32_e32 v215, 0xffff0000, v74
	v_lshlrev_b32_e32 v216, 16, v75
	v_and_b32_e32 v217, 0xffff0000, v75
	v_lshl_or_b32 v73, v163, 16, v162
	v_lshl_or_b32 v74, v169, 16, v168
	v_lshl_or_b32 v75, v171, 16, v170
	v_lshlrev_b32_e32 v162, 16, v69
	v_and_b32_e32 v163, 0xffff0000, v69
	v_lshlrev_b32_e32 v168, 16, v56
	v_and_b32_e32 v169, 0xffff0000, v56
	v_lshlrev_b32_e32 v170, 16, v57
	v_and_b32_e32 v171, 0xffff0000, v57
	s_mov_b32 s60, s17
	v_add_f32_e32 v152, v152, v160
	v_add_f32_e32 v153, v153, v160
	v_mul_f32_e32 v152, v152, v209
	v_mul_f32_e32 v80, v153, v80
	v_cvt_pk_bf16_f32 v80, v152, v80
	v_lshlrev_b32_e32 v152, 16, v81
	v_add_f32_e32 v153, v154, v160
	v_mul_f32_e32 v152, v153, v152
	v_and_b32_e32 v81, 0xffff0000, v81
	v_add_f32_e32 v153, v155, v160
	v_mul_f32_e32 v81, v153, v81
	v_cvt_pk_bf16_f32 v81, v152, v81
	v_lshlrev_b32_e32 v152, 16, v82
	v_add_f32_e32 v124, v124, v160
	v_and_b32_e32 v82, 0xffff0000, v82
	v_add_f32_e32 v125, v125, v160
	v_mul_f32_e32 v124, v124, v152
	v_mul_f32_e32 v82, v125, v82
	v_cvt_pk_bf16_f32 v82, v124, v82
	v_lshlrev_b32_e32 v124, 16, v83
	v_add_f32_e32 v125, v126, v160
	v_mul_f32_e32 v124, v125, v124
	v_and_b32_e32 v83, 0xffff0000, v83
	v_add_f32_e32 v125, v127, v160
	v_mul_f32_e32 v83, v125, v83
	v_cvt_pk_bf16_f32 v83, v124, v83
	global_store_dwordx4 v[132:133], v[80:83], off
	v_mov_b32_e32 v126, v232
	ds_read_b128 v[80:83], v151 offset:4352
	v_lshlrev_b32_e32 v127, 16, v76
	v_and_b32_e32 v152, 0xffff0000, v76
	v_lshlrev_b32_e32 v153, 16, v77
	v_and_b32_e32 v154, 0xffff0000, v77
	v_lshlrev_b32_e32 v155, 16, v78
	v_and_b32_e32 v160, 0xffff0000, v78
	v_lshlrev_b32_e32 v209, 16, v79
	s_waitcnt lgkmcnt(0)
	v_mfma_f32_16x16x32_bf16 v[76:79], v[120:123], v[80:83], 0
	v_add_co_u32_e32 v124, vcc, s56, v132
	v_mfma_f32_16x16x32_bf16 v[80:83], v[116:119], v[80:83], 0
	s_nop 0
	v_addc_co_u32_e32 v125, vcc, 0, v133, vcc
	s_nop 2
	v_add_f32_e32 v76, v76, v126
	v_add_f32_e32 v77, v77, v126
	v_add_f32_e32 v78, v78, v126
	v_add_f32_e32 v79, v79, v126
	v_add_f32_e32 v80, v80, v126
	v_add_f32_e32 v81, v81, v126
	v_add_f32_e32 v82, v82, v126
	v_add_f32_e32 v83, v83, v126
	v_mul_f32_e32 v76, v76, v127
	v_mul_f32_e32 v77, v77, v152
	v_mul_f32_e32 v78, v78, v153
	v_mul_f32_e32 v79, v79, v154
	v_mul_f32_e32 v80, v80, v155
	v_mul_f32_e32 v81, v81, v160
	v_mul_f32_e32 v82, v82, v209
	v_mul_f32_e32 v83, v83, v210
	v_cvt_pk_bf16_f32 v76, v76, v77
	v_cvt_pk_bf16_f32 v77, v78, v79
	v_cvt_pk_bf16_f32 v78, v80, v81
	v_cvt_pk_bf16_f32 v79, v82, v83
	global_store_dwordx4 v[124:125], v[76:79], off
	v_mov_b32_e32 v209, v233
	ds_read_b128 v[78:81], v151 offset:8704
	ds_read_b128 v[124:127], v151 offset:8768
	s_waitcnt lgkmcnt(1)
	v_mfma_f32_16x16x32_bf16 v[152:155], v[120:123], v[78:81], 0
	v_lshl_or_b32 v76, v166, 16, v167
	v_lshl_or_b32 v77, v164, 16, v165
	v_lshlrev_b32_e32 v210, 16, v72
	v_mfma_f32_16x16x32_bf16 v[80:83], v[116:119], v[78:81], 0
	v_lshl_or_b32 v78, v174, 16, v175
	v_lshl_or_b32 v79, v172, 16, v173
	v_lshl_or_b32 v72, v161, 16, v131
	v_add_co_u32_e32 v160, vcc, s55, v132
	s_waitcnt lgkmcnt(0)
	v_mfma_f32_16x16x32_bf16 v[80:83], v[76:79], v[124:127], v[80:83]
	v_addc_co_u32_e32 v161, vcc, 0, v133, vcc
	v_lshlrev_b32_e32 v164, 16, v70
	v_mfma_f32_16x16x32_bf16 v[152:155], v[72:75], v[124:127], v[152:155]
	v_and_b32_e32 v165, 0xffff0000, v70
	v_lshlrev_b32_e32 v166, 16, v71
	v_and_b32_e32 v167, 0xffff0000, v71
	v_lshlrev_b32_e32 v172, 16, v58
	v_add_f32_e32 v83, v83, v209
	s_nop 1
	v_add_f32_e32 v124, v152, v209
	v_add_f32_e32 v125, v153, v209
	v_add_f32_e32 v126, v154, v209
	v_add_f32_e32 v127, v155, v209
	v_add_f32_e32 v80, v80, v209
	v_add_f32_e32 v81, v81, v209
	v_add_f32_e32 v82, v82, v209
	v_mul_f32_e32 v83, v83, v217
	v_mul_f32_e32 v124, v124, v210
	v_mul_f32_e32 v125, v125, v211
	v_mul_f32_e32 v126, v126, v212
	v_mul_f32_e32 v127, v127, v213
	v_mul_f32_e32 v131, v80, v214
	v_mul_f32_e32 v152, v81, v215
	v_mul_f32_e32 v153, v82, v216
	v_cvt_pk_bf16_f32 v80, v124, v125
	v_cvt_pk_bf16_f32 v81, v126, v127
	v_cvt_pk_bf16_f32 v82, v131, v152
	v_cvt_pk_bf16_f32 v83, v153, v83
	global_store_dwordx4 v[160:161], v[80:83], off
	v_mov_b32_e32 v131, v234
	ds_read_b128 v[80:83], v151 offset:13056
	ds_read_b128 v[124:127], v151 offset:13120
	s_waitcnt lgkmcnt(1)
	v_mfma_f32_16x16x32_bf16 v[152:155], v[120:123], v[80:83], 0
	v_lshlrev_b32_e32 v160, 16, v68
	v_and_b32_e32 v161, 0xffff0000, v68
	v_mfma_f32_16x16x32_bf16 v[80:83], v[116:119], v[80:83], 0
	s_waitcnt lgkmcnt(0)
	v_mfma_f32_16x16x32_bf16 v[68:71], v[72:75], v[124:127], v[152:155]
	v_mfma_f32_16x16x32_bf16 v[80:83], v[76:79], v[124:127], v[80:83]
	s_nop 1
	v_add_co_u32_e32 v152, vcc, s54, v132
	s_nop 2
	v_add_f32_e32 v68, v68, v131
	v_add_f32_e32 v69, v69, v131
	v_add_f32_e32 v70, v70, v131
	v_add_f32_e32 v71, v71, v131
	v_addc_co_u32_e32 v153, vcc, 0, v133, vcc
	v_add_f32_e32 v80, v80, v131
	v_add_f32_e32 v81, v81, v131
	v_add_f32_e32 v82, v82, v131
	v_add_f32_e32 v83, v83, v131
	v_mul_f32_e32 v68, v68, v160
	v_mul_f32_e32 v69, v69, v161
	v_mul_f32_e32 v70, v70, v162
	v_mul_f32_e32 v71, v71, v163
	v_mul_f32_e32 v80, v80, v164
	v_mul_f32_e32 v81, v81, v165
	v_mul_f32_e32 v82, v82, v166
	v_mul_f32_e32 v83, v83, v167
	v_cvt_pk_bf16_f32 v68, v68, v69
	v_cvt_pk_bf16_f32 v69, v70, v71
	v_cvt_pk_bf16_f32 v70, v80, v81
	v_cvt_pk_bf16_f32 v71, v82, v83
	global_store_dwordx4 v[152:153], v[68:71], off
	v_mov_b32_e32 v131, v235
	ds_read_b128 v[68:71], v151 offset:17408
	ds_read_b128 v[152:155], v151 offset:17472
	s_waitcnt lgkmcnt(1)
	v_mfma_f32_16x16x32_bf16 v[124:127], v[120:123], v[68:71], 0
	v_lshl_or_b32 v80, v177, 16, v176
	v_lshl_or_b32 v81, v179, 16, v178
	v_lshl_or_b32 v82, v186, 16, v185
	v_mfma_f32_16x16x32_bf16 v[68:71], v[116:119], v[68:71], 0
	v_lshl_or_b32 v83, v188, 16, v187
	ds_read_b128 v[164:167], v151 offset:17536
	s_waitcnt lgkmcnt(1)
	v_mfma_f32_16x16x32_bf16 v[160:163], v[72:75], v[152:155], v[124:127]
	s_nop 2
	v_lshl_or_b32 v124, v182, 16, v183
	v_lshl_or_b32 v125, v180, 16, v181
	v_lshl_or_b32 v126, v191, 16, v192
	v_lshl_or_b32 v127, v189, 16, v190
	v_mfma_f32_16x16x32_bf16 v[68:71], v[76:79], v[152:155], v[68:71]
	s_waitcnt lgkmcnt(0)
	v_mfma_f32_16x16x32_bf16 v[152:155], v[80:83], v[164:167], v[160:163]
	s_nop 2
	v_and_b32_e32 v160, 0xffff0000, v58
	v_lshlrev_b32_e32 v161, 16, v59
	v_and_b32_e32 v162, 0xffff0000, v59
	v_mfma_f32_16x16x32_bf16 v[56:59], v[124:127], v[164:167], v[68:71]
	v_lshlrev_b32_e32 v164, 16, v48
	v_and_b32_e32 v165, 0xffff0000, v48
	v_lshlrev_b32_e32 v166, 16, v49
	v_and_b32_e32 v167, 0xffff0000, v49
	v_add_f32_e32 v68, v152, v131
	s_nop 1
	v_add_f32_e32 v57, v57, v131
	v_add_f32_e32 v58, v58, v131
	v_add_f32_e32 v59, v59, v131
	v_mul_f32_e32 v152, v57, v160
	v_add_co_u32_e32 v160, vcc, s53, v132
	v_add_f32_e32 v69, v153, v131
	v_add_f32_e32 v70, v154, v131
	v_add_f32_e32 v71, v155, v131
	v_add_f32_e32 v56, v56, v131
	v_mul_f32_e32 v153, v58, v161
	v_mul_f32_e32 v59, v59, v162
	v_addc_co_u32_e32 v161, vcc, 0, v133, vcc
	v_mul_f32_e32 v68, v68, v168
	v_mul_f32_e32 v69, v69, v169
	v_mul_f32_e32 v70, v70, v170
	v_mul_f32_e32 v71, v71, v171
	v_mul_f32_e32 v131, v56, v172
	v_cvt_pk_bf16_f32 v56, v68, v69
	v_cvt_pk_bf16_f32 v57, v70, v71
	v_cvt_pk_bf16_f32 v58, v131, v152
	v_cvt_pk_bf16_f32 v59, v153, v59
	global_store_dwordx4 v[160:161], v[56:59], off
	v_mov_b32_e32 v131, v236
	ds_read_b128 v[68:71], v151 offset:21760
	ds_read_b128 v[152:155], v151 offset:21824
	s_waitcnt lgkmcnt(1)
	v_mfma_f32_16x16x32_bf16 v[56:59], v[120:123], v[68:71], 0
	ds_read_b128 v[160:163], v151 offset:21888
	v_lshlrev_b32_e32 v168, 16, v50
	v_and_b32_e32 v169, 0xffff0000, v51
	v_mfma_f32_16x16x32_bf16 v[68:71], v[116:119], v[68:71], 0
	v_lshlrev_b32_e32 v170, 16, v19
	v_and_b32_e32 v171, 0xffff0000, v19
	s_waitcnt lgkmcnt(1)
	v_mfma_f32_16x16x32_bf16 v[56:59], v[72:75], v[152:155], v[56:59]
	v_mfma_f32_16x16x32_bf16 v[68:71], v[76:79], v[152:155], v[68:71]
	v_and_b32_e32 v154, 0xffff0000, v50
	v_lshlrev_b32_e32 v155, 16, v51
	v_add_co_u32_e32 v152, vcc, s52, v132
	s_waitcnt lgkmcnt(0)
	v_mfma_f32_16x16x32_bf16 v[48:51], v[80:83], v[160:163], v[56:59]
	v_addc_co_u32_e32 v153, vcc, 0, v133, vcc
	v_mfma_f32_16x16x32_bf16 v[56:59], v[124:127], v[160:163], v[68:71]
	v_lshl_or_b32 v160, v199, 16, v200
	v_lshl_or_b32 v161, v197, 16, v198
	v_lshl_or_b32 v162, v207, 16, v208
	v_lshl_or_b32 v163, v205, 16, v206
	s_nop 0
	v_add_f32_e32 v48, v48, v131
	v_add_f32_e32 v49, v49, v131
	v_add_f32_e32 v50, v50, v131
	v_add_f32_e32 v51, v51, v131
	v_add_f32_e32 v56, v56, v131
	v_add_f32_e32 v57, v57, v131
	v_add_f32_e32 v58, v58, v131
	v_add_f32_e32 v59, v59, v131
	v_mul_f32_e32 v48, v48, v164
	v_mul_f32_e32 v49, v49, v165
	v_mul_f32_e32 v50, v50, v166
	v_mul_f32_e32 v51, v51, v167
	v_mul_f32_e32 v56, v56, v168
	v_mul_f32_e32 v57, v57, v154
	v_mul_f32_e32 v58, v58, v155
	v_mul_f32_e32 v59, v59, v169
	v_cvt_pk_bf16_f32 v48, v48, v49
	v_cvt_pk_bf16_f32 v49, v50, v51
	v_cvt_pk_bf16_f32 v50, v56, v57
	v_cvt_pk_bf16_f32 v51, v58, v59
	global_store_dwordx4 v[152:153], v[48:51], off
	v_mov_b32_e32 v131, v237
	ds_read_b128 v[48:51], v151 offset:26112
	ds_read_b128 v[56:59], v151 offset:26176
	s_waitcnt lgkmcnt(1)
	v_mfma_f32_16x16x32_bf16 v[68:71], v[120:123], v[48:51], 0
	v_lshlrev_b32_e32 v164, 16, v16
	v_and_b32_e32 v165, 0xffff0000, v16
	v_lshlrev_b32_e32 v166, 16, v17
	v_mfma_f32_16x16x32_bf16 v[48:51], v[116:119], v[48:51], 0
	v_and_b32_e32 v167, 0xffff0000, v17
	v_lshlrev_b32_e32 v168, 16, v18
	v_and_b32_e32 v169, 0xffff0000, v18
	ds_read_b128 v[16:19], v151 offset:26240
	s_waitcnt lgkmcnt(1)
	v_mfma_f32_16x16x32_bf16 v[68:71], v[72:75], v[56:59], v[68:71]
	v_lshl_or_b32 v152, v194, 16, v193
	v_lshl_or_b32 v153, v196, 16, v195
	v_lshl_or_b32 v154, v202, 16, v201
	v_mfma_f32_16x16x32_bf16 v[48:51], v[76:79], v[56:59], v[48:51]
	ds_read_b128 v[56:59], v151 offset:26304
	v_lshl_or_b32 v155, v204, 16, v203
	s_waitcnt lgkmcnt(1)
	v_mfma_f32_16x16x32_bf16 v[68:71], v[80:83], v[16:19], v[68:71]
	v_mfma_f32_16x16x32_bf16 v[16:19], v[124:127], v[16:19], v[48:51]
	s_waitcnt lgkmcnt(0)
	v_mfma_f32_16x16x32_bf16 v[16:19], v[160:163], v[56:59], v[16:19]
	v_mfma_f32_16x16x32_bf16 v[48:51], v[152:155], v[56:59], v[68:71]
	s_nop 3
	v_add_co_u32_e32 v68, vcc, s35, v132
	s_nop 0
	v_add_f32_e32 v19, v19, v131
	v_addc_co_u32_e32 v69, vcc, 0, v133, vcc
	v_add_f32_e32 v48, v48, v131
	v_add_f32_e32 v49, v49, v131
	v_add_f32_e32 v50, v50, v131
	v_add_f32_e32 v51, v51, v131
	v_add_f32_e32 v16, v16, v131
	v_add_f32_e32 v17, v17, v131
	v_add_f32_e32 v18, v18, v131
	v_mul_f32_e32 v19, v19, v171
	v_mul_f32_e32 v48, v48, v164
	v_mul_f32_e32 v49, v49, v165
	v_mul_f32_e32 v50, v50, v166
	v_mul_f32_e32 v51, v51, v167
	v_mul_f32_e32 v56, v16, v168
	v_mul_f32_e32 v57, v17, v169
	v_mul_f32_e32 v58, v18, v170
	v_cvt_pk_bf16_f32 v16, v48, v49
	v_cvt_pk_bf16_f32 v17, v50, v51
	v_cvt_pk_bf16_f32 v18, v56, v57
	v_cvt_pk_bf16_f32 v19, v58, v19
	global_store_dwordx4 v[68:69], v[16:19], off
	v_mov_b32_e32 v0, v238
	ds_read_b128 v[16:19], v151 offset:30464
	ds_read_b128 v[56:59], v151 offset:30528
	s_waitcnt lgkmcnt(1)
	v_mfma_f32_16x16x32_bf16 v[48:51], v[120:123], v[16:19], 0
	v_lshlrev_b32_e32 v131, 16, v12
	v_and_b32_e32 v164, 0xffff0000, v12
	v_lshlrev_b32_e32 v165, 16, v13
	v_mfma_f32_16x16x32_bf16 v[68:71], v[116:119], v[16:19], 0
	s_waitcnt vmcnt(7)
	v_mov_b64_e32 v[16:17], v[108:109]
	v_mov_b64_e32 v[18:19], v[110:111]
	v_and_b32_e32 v166, 0xffff0000, v13
	s_waitcnt lgkmcnt(0)
	v_mfma_f32_16x16x32_bf16 v[72:75], v[72:75], v[56:59], v[48:51]
	v_lshlrev_b32_e32 v120, 16, v14
	v_and_b32_e32 v121, 0xffff0000, v14
	v_lshlrev_b32_e32 v122, 16, v15
	v_mov_b64_e32 v[48:49], v[104:105]
	v_mov_b64_e32 v[50:51], v[106:107]
	ds_read_b128 v[104:107], v151 offset:30592
	v_mfma_f32_16x16x32_bf16 v[108:111], v[76:79], v[56:59], v[68:71]
	v_mov_b64_e32 v[56:57], v[100:101]
	v_mov_b64_e32 v[58:59], v[102:103]
	v_mov_b64_e32 v[76:77], v[88:89]
	v_mov_b64_e32 v[68:69], v[96:97]
	v_mov_b64_e32 v[70:71], v[98:99]
	ds_read_b128 v[96:99], v151 offset:30656
	s_waitcnt lgkmcnt(1)
	v_mfma_f32_16x16x32_bf16 v[100:103], v[80:83], v[104:107], v[72:75]
	v_mov_b64_e32 v[80:81], v[84:85]
	v_mov_b64_e32 v[82:83], v[86:87]
	v_mov_b64_e32 v[78:79], v[90:91]
	v_mfma_f32_16x16x32_bf16 v[84:87], v[124:127], v[104:107], v[108:111]
	v_mov_b64_e32 v[72:73], v[92:93]
	v_mov_b64_e32 v[74:75], v[94:95]
	v_add_co_u32_e32 v92, vcc, 0x70000, v132
	s_waitcnt lgkmcnt(0)
	v_mfma_f32_16x16x32_bf16 v[88:91], v[152:155], v[96:99], v[100:103]
	v_and_b32_e32 v116, 0xffff0000, v15
	v_mov_b64_e32 v[12:13], v[112:113]
	v_addc_co_u32_e32 v93, vcc, 0, v133, vcc
	v_mfma_f32_16x16x32_bf16 v[84:87], v[160:163], v[96:99], v[84:87]
	v_mov_b64_e32 v[14:15], v[114:115]
	s_andn2_b64 vcc, exec, s[12:13]
	s_nop 0
	v_add_f32_e32 v88, v88, v0
	v_add_f32_e32 v89, v89, v0
	v_add_f32_e32 v90, v90, v0
	v_add_f32_e32 v91, v91, v0
	v_add_f32_e32 v84, v84, v0
	v_add_f32_e32 v85, v85, v0
	v_add_f32_e32 v86, v86, v0
	v_add_f32_e32 v0, v87, v0
	v_mul_f32_e32 v87, v88, v131
	v_mul_f32_e32 v88, v89, v164
	v_mul_f32_e32 v89, v90, v165
	v_mul_f32_e32 v90, v91, v166
	v_mul_f32_e32 v91, v84, v120
	v_mul_f32_e32 v94, v85, v121
	v_mul_f32_e32 v95, v86, v122
	v_mul_f32_e32 v0, v0, v116
	v_cvt_pk_bf16_f32 v84, v87, v88
	v_cvt_pk_bf16_f32 v85, v89, v90
	v_cvt_pk_bf16_f32 v86, v91, v94
	v_cvt_pk_bf16_f32 v87, v95, v0
	global_store_dwordx4 v[92:93], v[84:87], off
	s_barrier
	s_cbranch_vccz .LBB0_369
.LBB0_356:
	s_and_b32 s61, s60, 7
	s_lshl_b32 s98, s61, 9
	v_lshl_or_b32 v230, v135, 2, s98
	global_load_dword v231, v230, s[26:27]
	global_load_dword v232, v230, s[26:27] offset:64
	global_load_dword v233, v230, s[26:27] offset:128
	global_load_dword v234, v230, s[26:27] offset:192
	global_load_dword v235, v230, s[26:27] offset:256
	global_load_dword v236, v230, s[26:27] offset:320
	global_load_dword v237, v230, s[26:27] offset:384
	global_load_dword v238, v230, s[26:27] offset:448
	s_cmp_eq_u32 s61, s16
	s_cbranch_scc1 .LBB0_363
	s_cmp_lt_i32 s16, 0
	s_cbranch_scc1 .LBB0_359
	s_barrier
